# v18 + FFN_DOWN k-loop: next-k-tile global loads issued between the MFMAs of each wave's own compute segment (half Y deferred, offset -128), ladder stays store-only
# speedup vs baseline: 1.0173x; 1.0029x over previous
.LBB0_114:
	s_andn2_saveexec_b64 s[48:49], s[48:49]
	s_cbranch_execz .LBB0_116
	s_and_b32 s40, s72, 0x10000
	v_add_u32_e32 v0, s40, v192
	v_or_b32_e32 v2, s40, v193
	v_add_u32_e32 v14, v0, v194
	v_add_u32_e32 v15, v0, v195
	v_add_u32_e32 v199, v0, v196
	v_add_u32_e32 v0, v0, v197
	v_add_u32_e32 v205, v2, v194
	v_add_u32_e32 v228, v2, v195
	v_add_u32_e32 v250, v2, v196
	v_add_u32_e32 v251, v2, v197
	s_add_i32 s40, s61, -1
	s_cmp_gt_u32 s40, 41
	s_cbranch_scc1 .Lgi_FFN_DOWN_yno
	s_setprio 1
	ds_read_b128 v[2:5], v14 offset:0
	ds_read_b128 v[6:9], v14 offset:4096
	ds_read_b128 v[10:13], v14 offset:8192
	ds_read_b128 v[208:211], v14 offset:12288
	ds_read_b128 v[242:245], v205 offset:0
	ds_read_b128 v[246:249], v205 offset:4096
	ds_read_b128 v[214:217], v15 offset:0
	ds_read_b128 v[230:233], v15 offset:4096
	ds_read_b128 v[234:237], v15 offset:8192
	ds_read_b128 v[238:241], v15 offset:12288
	s_waitcnt lgkmcnt(4)
	v_mfma_f32_32x32x16_bf16 v[128:143], v[2:5], v[242:245], v[128:143]
	v_lshl_add_u64 v[212:213], v[190:191], 0, s[20:21]
	global_load_dwordx4 v[144:147], v[212:213], off offset:-128
	v_mfma_f32_32x32x16_bf16 v[96:111], v[6:9], v[242:245], v[96:111]
	v_mfma_f32_32x32x16_bf16 v[64:79], v[10:13], v[242:245], v[64:79]
	v_lshl_add_u64 v[212:213], v[182:183], 0, s[20:21]
	global_load_dwordx4 v[148:151], v[212:213], off offset:-128
	v_mfma_f32_32x32x16_bf16 v[32:47], v[208:211], v[242:245], v[32:47]
	ds_read_b128 v[242:245], v228 offset:0
	v_mfma_f32_32x32x16_bf16 v[112:127], v[2:5], v[246:249], v[112:127]
	v_lshl_add_u64 v[212:213], v[188:189], 0, s[20:21]
	global_load_dwordx4 v[152:155], v[212:213], off offset:-128
	v_mfma_f32_32x32x16_bf16 v[80:95], v[6:9], v[246:249], v[80:95]
	v_mfma_f32_32x32x16_bf16 v[48:63], v[10:13], v[246:249], v[48:63]
	v_lshl_add_u64 v[212:213], v[180:181], 0, s[20:21]
	global_load_dwordx4 v[156:159], v[212:213], off offset:-128
	v_mfma_f32_32x32x16_bf16 v[16:31], v[208:211], v[246:249], v[16:31]
	ds_read_b128 v[246:249], v228 offset:4096
	ds_read_b128 v[2:5], v199 offset:0
	ds_read_b128 v[6:9], v199 offset:4096
	ds_read_b128 v[10:13], v199 offset:8192
	ds_read_b128 v[208:211], v199 offset:12288
	s_waitcnt lgkmcnt(5)
	v_mfma_f32_32x32x16_bf16 v[128:143], v[214:217], v[242:245], v[128:143]
	v_lshl_add_u64 v[212:213], v[186:187], 0, s[20:21]
	global_load_dwordx4 v[160:163], v[212:213], off offset:-128
	v_mfma_f32_32x32x16_bf16 v[96:111], v[230:233], v[242:245], v[96:111]
	v_mfma_f32_32x32x16_bf16 v[64:79], v[234:237], v[242:245], v[64:79]
	v_lshl_add_u64 v[212:213], v[178:179], 0, s[20:21]
	global_load_dwordx4 v[164:167], v[212:213], off offset:-128
	v_mfma_f32_32x32x16_bf16 v[32:47], v[238:241], v[242:245], v[32:47]
	ds_read_b128 v[242:245], v250 offset:0
	s_waitcnt lgkmcnt(5)
	v_mfma_f32_32x32x16_bf16 v[112:127], v[214:217], v[246:249], v[112:127]
	v_lshl_add_u64 v[212:213], v[184:185], 0, s[20:21]
	global_load_dwordx4 v[168:171], v[212:213], off offset:-128
	v_mfma_f32_32x32x16_bf16 v[80:95], v[230:233], v[246:249], v[80:95]
	v_mfma_f32_32x32x16_bf16 v[48:63], v[234:237], v[246:249], v[48:63]
	v_lshl_add_u64 v[212:213], v[176:177], 0, s[20:21]
	global_load_dwordx4 v[172:175], v[212:213], off offset:-128
	v_mfma_f32_32x32x16_bf16 v[16:31], v[238:241], v[246:249], v[16:31]
	ds_read_b128 v[246:249], v250 offset:4096
	ds_read_b128 v[214:217], v0 offset:0
	ds_read_b128 v[230:233], v0 offset:4096
	ds_read_b128 v[234:237], v0 offset:8192
	ds_read_b128 v[238:241], v0 offset:12288
	s_waitcnt lgkmcnt(5)
	v_mfma_f32_32x32x16_bf16 v[128:143], v[2:5], v[242:245], v[128:143]
	v_mfma_f32_32x32x16_bf16 v[96:111], v[6:9], v[242:245], v[96:111]
	v_mfma_f32_32x32x16_bf16 v[64:79], v[10:13], v[242:245], v[64:79]
	v_mfma_f32_32x32x16_bf16 v[32:47], v[208:211], v[242:245], v[32:47]
	ds_read_b128 v[242:245], v251 offset:0
	s_waitcnt lgkmcnt(5)
	v_mfma_f32_32x32x16_bf16 v[112:127], v[2:5], v[246:249], v[112:127]
	v_mfma_f32_32x32x16_bf16 v[80:95], v[6:9], v[246:249], v[80:95]
	v_mfma_f32_32x32x16_bf16 v[48:63], v[10:13], v[246:249], v[48:63]
	v_mfma_f32_32x32x16_bf16 v[16:31], v[208:211], v[246:249], v[16:31]
	ds_read_b128 v[246:249], v251 offset:4096
	s_waitcnt lgkmcnt(1)
	v_mfma_f32_32x32x16_bf16 v[128:143], v[214:217], v[242:245], v[128:143]
	v_mfma_f32_32x32x16_bf16 v[96:111], v[230:233], v[242:245], v[96:111]
	v_mfma_f32_32x32x16_bf16 v[64:79], v[234:237], v[242:245], v[64:79]
	v_mfma_f32_32x32x16_bf16 v[32:47], v[238:241], v[242:245], v[32:47]
	s_waitcnt lgkmcnt(0)
	v_mfma_f32_32x32x16_bf16 v[112:127], v[214:217], v[246:249], v[112:127]
	v_mfma_f32_32x32x16_bf16 v[80:95], v[230:233], v[246:249], v[80:95]
	v_mfma_f32_32x32x16_bf16 v[48:63], v[234:237], v[246:249], v[48:63]
	v_mfma_f32_32x32x16_bf16 v[16:31], v[238:241], v[246:249], v[16:31]
	s_nop 15
	s_nop 7

	s_setprio 0
	s_branch .Lgi_FFN_DOWN_yend
.Lgi_FFN_DOWN_yno:
	s_setprio 1
	ds_read_b128 v[2:5], v14 offset:0
	ds_read_b128 v[6:9], v14 offset:4096
	ds_read_b128 v[10:13], v14 offset:8192
	ds_read_b128 v[208:211], v14 offset:12288
	ds_read_b128 v[242:245], v205 offset:0
	ds_read_b128 v[246:249], v205 offset:4096
	ds_read_b128 v[214:217], v15 offset:0
	ds_read_b128 v[230:233], v15 offset:4096
	ds_read_b128 v[234:237], v15 offset:8192
	ds_read_b128 v[238:241], v15 offset:12288
	s_waitcnt lgkmcnt(4)
	v_mfma_f32_32x32x16_bf16 v[128:143], v[2:5], v[242:245], v[128:143]
	v_mfma_f32_32x32x16_bf16 v[96:111], v[6:9], v[242:245], v[96:111]
	v_mfma_f32_32x32x16_bf16 v[64:79], v[10:13], v[242:245], v[64:79]
	v_mfma_f32_32x32x16_bf16 v[32:47], v[208:211], v[242:245], v[32:47]
	ds_read_b128 v[242:245], v228 offset:0
	v_mfma_f32_32x32x16_bf16 v[112:127], v[2:5], v[246:249], v[112:127]
	v_mfma_f32_32x32x16_bf16 v[80:95], v[6:9], v[246:249], v[80:95]
	v_mfma_f32_32x32x16_bf16 v[48:63], v[10:13], v[246:249], v[48:63]
	v_mfma_f32_32x32x16_bf16 v[16:31], v[208:211], v[246:249], v[16:31]
	ds_read_b128 v[246:249], v228 offset:4096
	ds_read_b128 v[2:5], v199 offset:0
	ds_read_b128 v[6:9], v199 offset:4096
	ds_read_b128 v[10:13], v199 offset:8192
	ds_read_b128 v[208:211], v199 offset:12288
	s_waitcnt lgkmcnt(5)
	v_mfma_f32_32x32x16_bf16 v[128:143], v[214:217], v[242:245], v[128:143]
	v_mfma_f32_32x32x16_bf16 v[96:111], v[230:233], v[242:245], v[96:111]
	v_mfma_f32_32x32x16_bf16 v[64:79], v[234:237], v[242:245], v[64:79]
	v_mfma_f32_32x32x16_bf16 v[32:47], v[238:241], v[242:245], v[32:47]
	ds_read_b128 v[242:245], v250 offset:0
	s_waitcnt lgkmcnt(5)
	v_mfma_f32_32x32x16_bf16 v[112:127], v[214:217], v[246:249], v[112:127]
	v_mfma_f32_32x32x16_bf16 v[80:95], v[230:233], v[246:249], v[80:95]
	v_mfma_f32_32x32x16_bf16 v[48:63], v[234:237], v[246:249], v[48:63]
	v_mfma_f32_32x32x16_bf16 v[16:31], v[238:241], v[246:249], v[16:31]
	ds_read_b128 v[246:249], v250 offset:4096
	ds_read_b128 v[214:217], v0 offset:0
	ds_read_b128 v[230:233], v0 offset:4096
	ds_read_b128 v[234:237], v0 offset:8192
	ds_read_b128 v[238:241], v0 offset:12288
	s_waitcnt lgkmcnt(5)
	v_mfma_f32_32x32x16_bf16 v[128:143], v[2:5], v[242:245], v[128:143]
	v_mfma_f32_32x32x16_bf16 v[96:111], v[6:9], v[242:245], v[96:111]
	v_mfma_f32_32x32x16_bf16 v[64:79], v[10:13], v[242:245], v[64:79]
	v_mfma_f32_32x32x16_bf16 v[32:47], v[208:211], v[242:245], v[32:47]
	ds_read_b128 v[242:245], v251 offset:0
	s_waitcnt lgkmcnt(5)
	v_mfma_f32_32x32x16_bf16 v[112:127], v[2:5], v[246:249], v[112:127]
	v_mfma_f32_32x32x16_bf16 v[80:95], v[6:9], v[246:249], v[80:95]
	v_mfma_f32_32x32x16_bf16 v[48:63], v[10:13], v[246:249], v[48:63]
	v_mfma_f32_32x32x16_bf16 v[16:31], v[208:211], v[246:249], v[16:31]
	ds_read_b128 v[246:249], v251 offset:4096
	s_waitcnt lgkmcnt(1)
	v_mfma_f32_32x32x16_bf16 v[128:143], v[214:217], v[242:245], v[128:143]
	v_mfma_f32_32x32x16_bf16 v[96:111], v[230:233], v[242:245], v[96:111]
	v_mfma_f32_32x32x16_bf16 v[64:79], v[234:237], v[242:245], v[64:79]
	v_mfma_f32_32x32x16_bf16 v[32:47], v[238:241], v[242:245], v[32:47]
	s_waitcnt lgkmcnt(0)
	v_mfma_f32_32x32x16_bf16 v[112:127], v[214:217], v[246:249], v[112:127]
	v_mfma_f32_32x32x16_bf16 v[80:95], v[230:233], v[246:249], v[80:95]
	v_mfma_f32_32x32x16_bf16 v[48:63], v[234:237], v[246:249], v[48:63]
	v_mfma_f32_32x32x16_bf16 v[16:31], v[238:241], v[246:249], v[16:31]
	s_nop 15
	s_nop 7

	s_setprio 0
.Lgi_FFN_DOWN_yend:
.LBB0_116:
	s_or_b64 exec, exec, s[48:49]
	s_and_saveexec_b64 s[40:41], s[46:47]
	s_xor_b64 s[48:49], exec, s[40:41]
	s_cbranch_execz .LBB0_121
	s_cmp_gt_u32 s61, 42
	s_cbranch_scc1 .LBB0_119
	s_add_i32 s40, s72, 0x10000
	s_and_b32 s40, s40, 0x10000
	v_add_u32_e32 v0, s40, v198
	s_waitcnt vmcnt(7)
	ds_write_b128 v0, v[144:147]
	s_waitcnt vmcnt(6)
	ds_write_b128 v0, v[148:151] offset:32768
	s_waitcnt vmcnt(5)
	ds_write_b128 v0, v[152:155] offset:8192
	s_waitcnt vmcnt(4)
	ds_write_b128 v0, v[156:159] offset:40960
	s_waitcnt vmcnt(3)
	ds_write_b128 v0, v[160:163] offset:16384
	s_waitcnt vmcnt(2)
	ds_write_b128 v0, v[164:167] offset:49152
	s_waitcnt vmcnt(1)
	ds_write_b128 v0, v[168:171] offset:24576
	s_waitcnt vmcnt(0)
	ds_write_b128 v0, v[172:175] offset:57344

.LBB0_121:
	s_andn2_saveexec_b64 s[48:49], s[48:49]
	s_cbranch_execz .LBB0_108
	s_and_b32 s40, s72, 0x10000
	v_add_u32_e32 v0, s40, v192
	v_or_b32_e32 v2, s40, v193
	v_add_u32_e32 v14, v0, v194
	v_add_u32_e32 v15, v0, v195
	v_add_u32_e32 v199, v0, v196
	v_add_u32_e32 v0, v0, v197
	v_add_u32_e32 v205, v2, v194
	v_add_u32_e32 v228, v2, v195
	v_add_u32_e32 v250, v2, v196
	v_add_u32_e32 v251, v2, v197
	s_cmp_gt_u32 s61, 41
	s_cbranch_scc1 .Lgi_FFN_DOWN_xno
	s_setprio 1
	ds_read_b128 v[2:5], v14 offset:0
	ds_read_b128 v[6:9], v14 offset:4096
	ds_read_b128 v[10:13], v14 offset:8192
	ds_read_b128 v[208:211], v14 offset:12288
	ds_read_b128 v[242:245], v205 offset:0
	ds_read_b128 v[246:249], v205 offset:4096
	ds_read_b128 v[214:217], v15 offset:0
	ds_read_b128 v[230:233], v15 offset:4096
	ds_read_b128 v[234:237], v15 offset:8192
	ds_read_b128 v[238:241], v15 offset:12288
	s_waitcnt lgkmcnt(4)
	v_mfma_f32_32x32x16_bf16 v[128:143], v[2:5], v[242:245], v[128:143]
	v_lshl_add_u64 v[212:213], v[190:191], 0, s[20:21]
	global_load_dwordx4 v[144:147], v[212:213], off
	v_mfma_f32_32x32x16_bf16 v[96:111], v[6:9], v[242:245], v[96:111]
	v_mfma_f32_32x32x16_bf16 v[64:79], v[10:13], v[242:245], v[64:79]
	v_lshl_add_u64 v[212:213], v[182:183], 0, s[20:21]
	global_load_dwordx4 v[148:151], v[212:213], off
	v_mfma_f32_32x32x16_bf16 v[32:47], v[208:211], v[242:245], v[32:47]
	ds_read_b128 v[242:245], v228 offset:0
	v_mfma_f32_32x32x16_bf16 v[112:127], v[2:5], v[246:249], v[112:127]
	v_lshl_add_u64 v[212:213], v[188:189], 0, s[20:21]
	global_load_dwordx4 v[152:155], v[212:213], off
	v_mfma_f32_32x32x16_bf16 v[80:95], v[6:9], v[246:249], v[80:95]
	v_mfma_f32_32x32x16_bf16 v[48:63], v[10:13], v[246:249], v[48:63]
	v_lshl_add_u64 v[212:213], v[180:181], 0, s[20:21]
	global_load_dwordx4 v[156:159], v[212:213], off
	v_mfma_f32_32x32x16_bf16 v[16:31], v[208:211], v[246:249], v[16:31]
	ds_read_b128 v[246:249], v228 offset:4096
	ds_read_b128 v[2:5], v199 offset:0
	ds_read_b128 v[6:9], v199 offset:4096
	ds_read_b128 v[10:13], v199 offset:8192
	ds_read_b128 v[208:211], v199 offset:12288
	s_waitcnt lgkmcnt(5)
	v_mfma_f32_32x32x16_bf16 v[128:143], v[214:217], v[242:245], v[128:143]
	v_lshl_add_u64 v[212:213], v[186:187], 0, s[20:21]
	global_load_dwordx4 v[160:163], v[212:213], off
	v_mfma_f32_32x32x16_bf16 v[96:111], v[230:233], v[242:245], v[96:111]
	v_mfma_f32_32x32x16_bf16 v[64:79], v[234:237], v[242:245], v[64:79]
	v_lshl_add_u64 v[212:213], v[178:179], 0, s[20:21]
	global_load_dwordx4 v[164:167], v[212:213], off
	v_mfma_f32_32x32x16_bf16 v[32:47], v[238:241], v[242:245], v[32:47]
	ds_read_b128 v[242:245], v250 offset:0
	s_waitcnt lgkmcnt(5)
	v_mfma_f32_32x32x16_bf16 v[112:127], v[214:217], v[246:249], v[112:127]
	v_lshl_add_u64 v[212:213], v[184:185], 0, s[20:21]
	global_load_dwordx4 v[168:171], v[212:213], off
	v_mfma_f32_32x32x16_bf16 v[80:95], v[230:233], v[246:249], v[80:95]
	v_mfma_f32_32x32x16_bf16 v[48:63], v[234:237], v[246:249], v[48:63]
	v_lshl_add_u64 v[212:213], v[176:177], 0, s[20:21]
	global_load_dwordx4 v[172:175], v[212:213], off
	v_mfma_f32_32x32x16_bf16 v[16:31], v[238:241], v[246:249], v[16:31]
	ds_read_b128 v[246:249], v250 offset:4096
	ds_read_b128 v[214:217], v0 offset:0
	ds_read_b128 v[230:233], v0 offset:4096
	ds_read_b128 v[234:237], v0 offset:8192
	ds_read_b128 v[238:241], v0 offset:12288
	s_waitcnt lgkmcnt(5)
	v_mfma_f32_32x32x16_bf16 v[128:143], v[2:5], v[242:245], v[128:143]
	v_mfma_f32_32x32x16_bf16 v[96:111], v[6:9], v[242:245], v[96:111]
	v_mfma_f32_32x32x16_bf16 v[64:79], v[10:13], v[242:245], v[64:79]
	v_mfma_f32_32x32x16_bf16 v[32:47], v[208:211], v[242:245], v[32:47]
	ds_read_b128 v[242:245], v251 offset:0
	s_waitcnt lgkmcnt(5)
	v_mfma_f32_32x32x16_bf16 v[112:127], v[2:5], v[246:249], v[112:127]
	v_mfma_f32_32x32x16_bf16 v[80:95], v[6:9], v[246:249], v[80:95]
	v_mfma_f32_32x32x16_bf16 v[48:63], v[10:13], v[246:249], v[48:63]
	v_mfma_f32_32x32x16_bf16 v[16:31], v[208:211], v[246:249], v[16:31]
	ds_read_b128 v[246:249], v251 offset:4096
	s_waitcnt lgkmcnt(1)
	v_mfma_f32_32x32x16_bf16 v[128:143], v[214:217], v[242:245], v[128:143]
	v_mfma_f32_32x32x16_bf16 v[96:111], v[230:233], v[242:245], v[96:111]
	v_mfma_f32_32x32x16_bf16 v[64:79], v[234:237], v[242:245], v[64:79]
	v_mfma_f32_32x32x16_bf16 v[32:47], v[238:241], v[242:245], v[32:47]
	s_waitcnt lgkmcnt(0)
	v_mfma_f32_32x32x16_bf16 v[112:127], v[214:217], v[246:249], v[112:127]
	v_mfma_f32_32x32x16_bf16 v[80:95], v[230:233], v[246:249], v[80:95]
	v_mfma_f32_32x32x16_bf16 v[48:63], v[234:237], v[246:249], v[48:63]
	v_mfma_f32_32x32x16_bf16 v[16:31], v[238:241], v[246:249], v[16:31]
	s_nop 15
	s_nop 7

	s_setprio 0
	s_branch .Lgi_FFN_DOWN_xend

.Lgi_FFN_DOWN_xend:
	s_branch .LBB0_108
.LBB0_123:
	v_xor_b32_e32 v212, 32, v227
	v_xor_b32_e32 v213, 16, v227
	s_cmp_lg_u64 s[30:31], 0
	s_cbranch_scc0 .LBB0_125
	s_mul_i32 s21, s78, 0x160000
	s_mul_hi_i32 s20, s78, 0x160000
	s_add_u32 s21, s50, s21
	s_addc_u32 s20, s51, s20
	v_mov_b32_e32 v0, s31
	v_mov_b32_e32 v2, s20
	v_cmp_lt_i32_e32 vcc, s76, v201
	s_movk_i32 s20, 0xb00
	s_nop 0
	v_cndmask_b32_e32 v3, v0, v2, vcc
	v_mov_b32_e32 v0, s30
	v_mov_b32_e32 v2, s21
	v_cndmask_b32_e32 v2, v0, v2, vcc
	v_mul_u32_u24_sdwa v0, v201, s20 dst_sel:DWORD dst_unused:UNUSED_PAD src0_sel:BYTE_0 src1_sel:DWORD
	v_lshlrev_b32_e32 v0, 1, v0
	v_lshl_add_u64 v[2:3], v[2:3], 0, v[0:1]
	global_load_dword v228, v[2:3], off
	global_load_dword v228, v[2:3], off offset:128
	s_branch .LBB0_126
